# attention: hand-scheduled far-path step body (branch-free, VALU in MFMA gaps, P fragments staged early), near steps keep general body; items remapped one head per XCD
# speedup vs baseline: 1.0065x; 1.0065x over previous
; template <int PROBE, int MODE>
; DI void dattn_body(const u16* __restrict__ Qb, const u16* __restrict__ Kh, const u16* __restrict__ Vh, u16* __restrict__ Ob, const u16* __restrict__ O1, float lam, const float* __restrict__ subg, int seq, int q0, float kmax2, char* lds) {
;   const int tid = otid(), wid = tid >> 6, lane = tid & 63, r32 = lane & 31, hi = lane >> 5, rg = wid >> 1, kh = wid & 1;
;   char* V_lds = lds + DA_V; char* K_lds = lds + DA_K; char* P_lds = lds + DA_P; float* lsum = (float*)(lds + DA_L); const float* tab = (const float*)(lds + DA_TAB);
;   constexpr float C = SCALE * LOG2E;
;   bf16x8 qr[8];
;   const u16* Qw = Qb + (long)(rg * 32 + r32) * DM + hi * 8;
; #pragma unroll
;   for (int d0 = 0; d0 < 8; ++d0) qr[d0] = ld8(Qw + d0 * 16);
;   float q2 = 0.f;
; #pragma unroll
;   for (int d0 = 0; d0 < 8; ++d0)
; #pragma unroll
;     for (int e = 0; e < 8; ++e) { const float f = bf2f((u16)qr[d0][e]); q2 = fmaf(f, f, q2); }
;   { auto rr = __builtin_amdgcn_permlane32_swap(__float_as_uint(q2), __float_as_uint(q2), false, false); q2 = __uint_as_float(rr[0]) + __uint_as_float(rr[1]); }
;   const int sr = tid >> 4, sc = (tid & 15) * 8, vst0 = v_st(sr, sc), vst1 = v_st(32 + sr, sc), kst0 = KSWZ(sr, sc * 2), kst1 = KSWZ(32 + sr, sc * 2);
;   const int vb0 = (int)(uintptr_t)V_lds + kh * 16384 + v_rd_base(lane);
;   const int qpos = q0 + rg * 32 + r32;
;   char* pw = P_lds + wid * 2048 + lane * 32;
;   const char* pr = P_lds + (wid ^ 1) * 2048 + lane * 32;
;   const int wu = __builtin_amdgcn_readfirstlane(wid);
;   unsigned koff[2], voff[2];
; #pragma unroll
;   for (int i = 0; i < 2; ++i) {
;     const int a = i * 8192 + wid * 1024 + lane * 16;
;     { const int row = a >> 8, pch = (a & 255) >> 4, c = pch ^ (row & 7); koff[i] = (unsigned)(row * DM + c * 8) * 2u; }
;     ...
;       for (int it = blockIdx.x; it < 1024 && sel != 2; it += gridDim.x) {
;         const int qb = it % nqb; const int r = it / nqb; const int h = r & 7, sq = r >> 3;
;         __syncthreads();
;         if (tid < 258) ((float*)(lds + DA_TAB))[tid] = gtab[h * 260 + tid];
;         const long t0 = (long)sq * slen, tq = t0 + qb * 128;
;         dattn_body<0, 0>(Q + tq * DM + h * 256, Kp + t0 * DM + h * 256, Vp + t0 * DM + h * 256,
;                          O1s + tq * DM + h * 256, nullptr, lam, p.subln_g, slen, qb * 128, kmax[sq * 16 + h * 2], lds);
.LBB0_227:
	s_and_b32 s100, s2, 7
	s_bfe_u32 s101, s2, 0x50003
	s_lshr_b32 s4, s2, 8
	s_lshl_b32 s4, s4, 5
	s_add_i32 s101, s101, s4
	s_ff1_i32_b32 s4, s80
	s_lshr_b32 s5, s101, s4
	s_lshl_b32 s5, s5, 3
	s_add_i32 s5, s5, s100
	s_lshl_b32 s5, s5, s4
	s_add_i32 s100, s80, -1
	s_and_b32 s101, s101, s100
	s_add_i32 s100, s5, s101
	s_abs_i32 s1, s100
	v_readlane_b32 s4, v255, 39
	s_mul_hi_u32 s4, s1, s4
	s_mul_i32 s5, s4, s80
	s_sub_i32 s1, s1, s5
	s_ashr_i32 s0, s100, 31
	s_add_i32 s5, s4, 1
	s_sub_i32 s14, s1, s80
	s_cmp_ge_u32 s1, s80
	s_cselect_b32 s4, s5, s4
	s_cselect_b32 s1, s14, s1
	s_add_i32 s5, s4, 1
	s_cmp_ge_u32 s1, s80
	s_cselect_b32 s1, s5, s4
	s_xor_b32 s1, s1, s0
	s_sub_i32 s41, s1, s0
	s_movk_i32 s22, 0x80
	s_and_b32 s33, s41, 7
	s_barrier
	s_mov_b64 s[0:1], exec
	v_readlane_b32 s4, v255, 35
	v_readlane_b32 s5, v255, 36
	s_and_b64 s[4:5], s[0:1], s[4:5]
	s_mov_b64 exec, s[4:5]
	s_cbranch_execz .LBB0_229
	s_mul_i32 s4, s33, 0x104
	v_add_u32_e32 v0, s4, v190
	v_readlane_b32 s4, v251, 6
	v_ashrrev_i32_e32 v1, 31, v0
	v_readlane_b32 s5, v251, 7
	s_nop 1
	v_lshl_add_u64 v[0:1], v[0:1], 2, s[4:5]
	global_load_dword v0, v[0:1], off
	s_waitcnt vmcnt(0)
	ds_write_b32 v174, v0
.LBB0_229:
	s_or_b64 exec, exec, s[0:1]
	s_mul_i32 s0, s41, s80
	s_sub_i32 s18, s100, s0
	s_ashr_i32 s0, s41, 3
	s_ashr_i32 s1, s0, 31
	v_readlane_b32 s4, v255, 37
	s_lshl_b32 s87, s18, 7
	s_lshl_b64 s[14:15], s[0:1], s4
	s_ashr_i32 s1, s87, 31
	s_add_u32 s46, s14, s87
	s_addc_u32 s47, s15, s1
	s_lshl_b64 s[4:5], s[46:47], 12
	v_readlane_b32 s16, v251, 29
	v_readlane_b32 s17, v251, 30
	s_add_u32 s1, s16, s4
	s_addc_u32 s5, s17, s5
	s_lshl_b32 s19, s33, 9
	s_add_u32 s4, s1, s19
	s_addc_u32 s5, s5, 0
	s_lshl_b64 s[16:17], s[14:15], 12
	s_add_u32 s1, s36, s16
	s_addc_u32 s15, s37, s17
	s_add_u32 s14, s1, s19
	s_addc_u32 s15, s15, 0
	v_readlane_b32 s20, v253, 14
	v_readlane_b32 s21, v253, 15
	s_add_u32 s1, s20, s16
	s_addc_u32 s17, s21, s17
	s_add_u32 s16, s1, s19
	s_addc_u32 s17, s17, 0
	s_lshl_b32 s0, s0, 4
	s_lshl_b32 s1, s33, 1
	s_or_b32 s0, s0, s1
	s_ashr_i32 s1, s0, 31
	s_lshl_b64 s[0:1], s[0:1], 2
	v_readlane_b32 s20, v251, 45
	v_readlane_b32 s21, v251, 46
	s_add_u32 s38, s20, s0
	s_addc_u32 s39, s21, s1
	v_mov_b32_e32 v175, v179
	global_load_dword v0, v177, s[38:39]
	s_movk_i32 s0, 0xffe0
	v_ashrrev_i32_e32 v22, 2, v175
	v_bfi_b32 v2, s0, v22, v175
	v_ashrrev_i32_e32 v3, 31, v2
	v_bfe_u32 v24, v175, 5, 1
	v_lshlrev_b64 v[2:3], 12, v[2:3]
	v_lshl_add_u64 v[2:3], s[4:5], 0, v[2:3]
	v_lshlrev_b32_e32 v16, 4, v24
	v_mov_b32_e32 v17, v177
	v_lshl_add_u64 v[2:3], v[2:3], 0, v[16:17]
	global_load_dwordx4 v[82:85], v[2:3], off
	global_load_dwordx4 v[86:89], v[2:3], off offset:32
	global_load_dwordx4 v[90:93], v[2:3], off offset:64
	global_load_dwordx4 v[94:97], v[2:3], off offset:96
	global_load_dwordx4 v[98:101], v[2:3], off offset:128
	global_load_dwordx4 v[102:105], v[2:3], off offset:160
	global_load_dwordx4 v[106:109], v[2:3], off offset:192
	global_load_dwordx4 v[110:113], v[2:3], off offset:224
	v_and_b32_e32 v193, 63, v175
	v_ashrrev_i32_e32 v194, 6, v175
	v_lshlrev_b32_e32 v17, 4, v193
	v_lshlrev_b32_e32 v3, 10, v194
	v_or_b32_e32 v6, v3, v17
	v_and_b32_e32 v4, 15, v175
	v_ashrrev_i32_e32 v7, 8, v6
	v_bitop3_b32 v8, v7, v4, 7 bitop3:0x6c
	v_lshlrev_b32_e32 v7, 12, v7
	v_lshl_or_b32 v152, v8, 4, v7
	v_ashrrev_i32_e32 v7, 4, v6
	v_lshlrev_b32_e32 v8, 2, v194
	v_bfe_u32 v9, v7, 2, 2
	v_and_b32_e32 v8, 0xffff0, v8
	v_lshrrev_b32_e32 v7, 1, v7
	v_lshlrev_b32_e32 v10, 1, v194
	v_and_b32_e32 v7, 8, v7
	v_and_or_b32 v8, v10, 4, v8
	v_or3_b32 v7, v8, v9, v7
	v_lshrrev_b32_e32 v6, 3, v6
	v_and_b32_e32 v5, 48, v17
	v_and_b32_e32 v6, 0xc0, v6
	v_lshlrev_b32_e32 v7, 12, v7
	v_add_u32_e32 v3, 0x2000, v3
	v_or3_b32 v176, v7, v6, v5
	v_or_b32_e32 v6, v3, v17
	v_ashrrev_i32_e32 v7, 8, v6
	v_bitop3_b32 v4, v7, v4, 7 bitop3:0x6c
	v_lshlrev_b32_e32 v7, 12, v7
	v_readfirstlane_b32 s0, v194
	v_lshl_or_b32 v154, v4, 4, v7
	v_ashrrev_i32_e32 v4, 4, v6
	v_ashrrev_i32_e32 v3, 8, v3
	s_lshl_b32 s0, s0, 10
	s_add_i32 s95, 16, 0x10000
	v_bfe_u32 v7, v4, 2, 2
	v_and_b32_e32 v8, 0xffff0, v3
	v_lshrrev_b32_e32 v4, 1, v4
	v_lshrrev_b32_e32 v3, 1, v3
	s_add_i32 s82, s95, s0
	v_and_b32_e32 v4, 8, v4
	v_and_or_b32 v3, v3, 4, v8
	s_mov_b32 m0, s82
	v_or3_b32 v3, v3, v7, v4
	v_lshrrev_b32_e32 v4, 3, v6
	global_load_lds_dwordx4 v152, s[14:15]
	s_add_i32 m0, s82, 0x2000
	s_add_i32 s85, s0, 16
	v_and_b32_e32 v4, 0xc0, v4
	v_lshlrev_b32_e32 v3, 12, v3
	global_load_lds_dwordx4 v154, s[14:15]
	s_mov_b32 m0, s85
	v_or3_b32 v156, v3, v4, v5
	global_load_lds_dwordx4 v176, s[16:17]
	s_add_i32 m0, s85, 0x2000
	v_mov_b32_e32 v157, v177
	global_load_lds_dwordx4 v156, s[16:17]
	s_add_i32 m0, s85, 0x4000
	v_lshl_add_u64 v[4:5], s[16:17], 0, v[156:157]
	v_and_b32_e32 v192, 31, v175
	v_and_b32_e32 v196, 1, v194
	v_lshlrev_b32_e32 v195, 4, v175
	v_and_b32_e32 v20, 0x70, v195
	v_bitop3_b32 v199, v16, v20, 32 bitop3:0x36
	v_bitop3_b32 v200, v16, v20, 64 bitop3:0x36
	v_bitop3_b32 v202, v16, v20, s22 bitop3:0x36
	s_waitcnt vmcnt(0)
; DI float bf2f(u16 v) { return __uint_as_float(((unsigned)v) << 16); }
; #define KDMA(k0, b) do { const char* g_ = (const char*)(Kh + (long)(k0) * DM); char* l_ = K_lds + (b) * 16384 + wu * 1024; \
;     DMA16(g_ + koff[0], l_); DMA16(g_ + koff[1], l_ + 8192); } while (0)
; #define VDMA(k0, b) do { const char* g_ = (const char*)(Vh + (long)(k0) * DM); char* l_ = V_lds + (b) * 32768 + wu * 1024; \
;     DMA16(g_ + voff[0], l_); DMA16(g_ + voff[1], l_ + 8192); DMA16(g_ + voff[0] + 256, l_ + 16384); DMA16(g_ + voff[1] + 256, l_ + 16384 + 8192); } while (0)
; #define DMAWAIT() asm volatile("s_waitcnt vmcnt(0)" ::: "memory")
; template <int PROBE, int MODE>
; DI void dattn_body(const u16* __restrict__ Qb, const u16* __restrict__ Kh, const u16* __restrict__ Vh, u16* __restrict__ Ob, const u16* __restrict__ O1, float lam, const float* __restrict__ subg, int seq, int q0, float kmax2, char* lds) {
;     ...
;   float q2 = 0.f;
; #pragma unroll
;   for (int d0 = 0; d0 < 8; ++d0)
; #pragma unroll
;     for (int e = 0; e < 8; ++e) { const float f = bf2f((u16)qr[d0][e]); q2 = fmaf(f, f, q2); }
;   { auto rr = __builtin_amdgcn_permlane32_swap(__float_as_uint(q2), __float_as_uint(q2), false, false); q2 = __uint_as_float(rr[0]) + __uint_as_float(rr[1]); }
;     ...
;   KDMA(0, 0); VDMA(0, 0); KDMA(KVBLK, 1);
;   DMAWAIT();
;   __syncthreads();
	v_lshlrev_b32_e32 v1, 16, v82
	v_fma_f32 v1, v1, v1, 0
	v_and_b32_e32 v2, 0xffff0000, v82
	v_fmac_f32_e32 v1, v2, v2
	v_lshlrev_b32_e32 v2, 16, v83
	v_fmac_f32_e32 v1, v2, v2
	v_and_b32_e32 v2, 0xffff0000, v83
	v_fmac_f32_e32 v1, v2, v2
	v_lshlrev_b32_e32 v2, 16, v84
	v_fmac_f32_e32 v1, v2, v2
	v_and_b32_e32 v2, 0xffff0000, v84
	v_fmac_f32_e32 v1, v2, v2
	v_lshlrev_b32_e32 v2, 16, v85
	v_fmac_f32_e32 v1, v2, v2
	v_and_b32_e32 v2, 0xffff0000, v85
	v_fmac_f32_e32 v1, v2, v2
	v_lshlrev_b32_e32 v2, 16, v86
	v_fmac_f32_e32 v1, v2, v2
	v_and_b32_e32 v2, 0xffff0000, v86
	v_fmac_f32_e32 v1, v2, v2
	v_lshlrev_b32_e32 v2, 16, v87
	v_fmac_f32_e32 v1, v2, v2
	v_and_b32_e32 v2, 0xffff0000, v87
	v_fmac_f32_e32 v1, v2, v2
	v_lshlrev_b32_e32 v2, 16, v88
	v_fmac_f32_e32 v1, v2, v2
	v_and_b32_e32 v2, 0xffff0000, v88
	v_fmac_f32_e32 v1, v2, v2
	v_lshlrev_b32_e32 v2, 16, v89
	v_fmac_f32_e32 v1, v2, v2
	v_and_b32_e32 v2, 0xffff0000, v89
	v_fmac_f32_e32 v1, v2, v2
	v_lshlrev_b32_e32 v2, 16, v90
	v_fmac_f32_e32 v1, v2, v2
	v_and_b32_e32 v2, 0xffff0000, v90
	v_fmac_f32_e32 v1, v2, v2
	v_lshlrev_b32_e32 v2, 16, v91
	v_fmac_f32_e32 v1, v2, v2
	v_and_b32_e32 v2, 0xffff0000, v91
	v_fmac_f32_e32 v1, v2, v2
	v_lshlrev_b32_e32 v2, 16, v92
	v_fmac_f32_e32 v1, v2, v2
	v_and_b32_e32 v2, 0xffff0000, v92
	v_fmac_f32_e32 v1, v2, v2
	v_lshlrev_b32_e32 v2, 16, v93
	v_fmac_f32_e32 v1, v2, v2
	v_and_b32_e32 v2, 0xffff0000, v93
	v_fmac_f32_e32 v1, v2, v2
	v_lshlrev_b32_e32 v2, 16, v94
	v_fmac_f32_e32 v1, v2, v2
	v_and_b32_e32 v2, 0xffff0000, v94
	v_fmac_f32_e32 v1, v2, v2
	v_lshlrev_b32_e32 v2, 16, v95
	v_fmac_f32_e32 v1, v2, v2
	v_and_b32_e32 v2, 0xffff0000, v95
	v_fmac_f32_e32 v1, v2, v2
	v_lshlrev_b32_e32 v2, 16, v96
	v_fmac_f32_e32 v1, v2, v2
	v_and_b32_e32 v2, 0xffff0000, v96
	v_fmac_f32_e32 v1, v2, v2
	v_lshlrev_b32_e32 v2, 16, v97
	v_fmac_f32_e32 v1, v2, v2
	v_and_b32_e32 v2, 0xffff0000, v97
	v_fmac_f32_e32 v1, v2, v2
	v_lshlrev_b32_e32 v2, 16, v98
	v_fmac_f32_e32 v1, v2, v2
	v_and_b32_e32 v2, 0xffff0000, v98
	v_fmac_f32_e32 v1, v2, v2
	v_lshlrev_b32_e32 v2, 16, v99
	v_fmac_f32_e32 v1, v2, v2
	v_and_b32_e32 v2, 0xffff0000, v99
	v_fmac_f32_e32 v1, v2, v2
	v_lshlrev_b32_e32 v2, 16, v100
	v_fmac_f32_e32 v1, v2, v2
	v_and_b32_e32 v2, 0xffff0000, v100
	v_fmac_f32_e32 v1, v2, v2
	v_lshlrev_b32_e32 v2, 16, v101
	v_fmac_f32_e32 v1, v2, v2
	v_and_b32_e32 v2, 0xffff0000, v101
	v_fmac_f32_e32 v1, v2, v2
	v_lshlrev_b32_e32 v2, 16, v102
	v_fmac_f32_e32 v1, v2, v2
	v_and_b32_e32 v2, 0xffff0000, v102
	v_fmac_f32_e32 v1, v2, v2
	v_lshlrev_b32_e32 v2, 16, v103
	v_fmac_f32_e32 v1, v2, v2
	v_and_b32_e32 v2, 0xffff0000, v103
	v_fmac_f32_e32 v1, v2, v2
	v_lshlrev_b32_e32 v2, 16, v104
	v_fmac_f32_e32 v1, v2, v2
	v_and_b32_e32 v2, 0xffff0000, v104
	v_fmac_f32_e32 v1, v2, v2
	v_lshlrev_b32_e32 v2, 16, v105
	v_fmac_f32_e32 v1, v2, v2
	v_and_b32_e32 v2, 0xffff0000, v105
	v_fmac_f32_e32 v1, v2, v2
	v_lshlrev_b32_e32 v2, 16, v106
	v_fmac_f32_e32 v1, v2, v2
	v_and_b32_e32 v2, 0xffff0000, v106
	v_fmac_f32_e32 v1, v2, v2
	v_lshlrev_b32_e32 v2, 16, v107
	v_fmac_f32_e32 v1, v2, v2
	v_and_b32_e32 v2, 0xffff0000, v107
	v_fmac_f32_e32 v1, v2, v2
	v_lshlrev_b32_e32 v2, 16, v108
	v_fmac_f32_e32 v1, v2, v2
	v_and_b32_e32 v2, 0xffff0000, v108
	v_fmac_f32_e32 v1, v2, v2
	v_lshlrev_b32_e32 v2, 16, v109
	v_fmac_f32_e32 v1, v2, v2
	v_and_b32_e32 v2, 0xffff0000, v109
	v_fmac_f32_e32 v1, v2, v2
	v_lshlrev_b32_e32 v2, 16, v110
	v_fmac_f32_e32 v1, v2, v2
	v_and_b32_e32 v2, 0xffff0000, v110
	v_fmac_f32_e32 v1, v2, v2
	v_lshlrev_b32_e32 v2, 16, v111
	v_fmac_f32_e32 v1, v2, v2
	v_and_b32_e32 v2, 0xffff0000, v111
	v_fmac_f32_e32 v1, v2, v2
	v_lshlrev_b32_e32 v2, 16, v112
	v_fmac_f32_e32 v1, v2, v2
	v_and_b32_e32 v2, 0xffff0000, v112
	v_fmac_f32_e32 v1, v2, v2
	v_lshlrev_b32_e32 v2, 16, v113
	v_fmac_f32_e32 v1, v2, v2
	v_and_b32_e32 v2, 0xffff0000, v113
	v_fmac_f32_e32 v1, v2, v2
	v_mov_b32_e32 v2, v1
	s_nop 1
	v_permlane32_swap_b32_e32 v1, v2
	v_add_f32_e32 v1, v1, v2
	v_lshl_add_u64 v[2:3], s[16:17], 0, v[176:177]
	v_lshl_add_u64 v[2:3], v[2:3], 0, s[8:9]
	global_load_lds_dwordx4 v[2:3], off
	s_add_i32 m0, s85, 0x6000
	v_lshl_add_u64 v[2:3], v[4:5], 0, s[8:9]
	s_add_u32 s0, s14, 0x40000
	global_load_lds_dwordx4 v[2:3], off
	s_addc_u32 s1, s15, 0
	s_add_i32 m0, s85, 0x14000
	v_mov_b32_e32 v2, s76
	global_load_lds_dwordx4 v152, s[0:1]
	s_add_i32 m0, s85, 0x16000
	v_mul_f32_e32 v0, v0, v1
	global_load_lds_dwordx4 v154, s[0:1]
	s_waitcnt vmcnt(0)
	s_waitcnt vmcnt(0) lgkmcnt(0)
	s_barrier
; #define QKH(b) do { S = f32x16{}; const char* Ks_ = K_lds + (b) * 16384; _Pragma("unroll") for (int d0 = 0; d0 < 8; ++d0) { \
;     const bf16x8 kf = *reinterpret_cast<const bf16x8*>(Ks_ + KSWZ(32 * kh + r32, (d0 * 16 + hi * 8) * 2)); \
;     S = __builtin_amdgcn_mfma_f32_32x32x16_bf16(kf, qr[d0], S, 0, 0, 0); } } while (0)
; #define SMX_FIN(pbuf) do { _Pragma("unroll") for (int r = 0; r < 16; ++r) l_reg += S[r]; \
;     PK4S(0, po0); PK4S(8, po1); \
;     *(bf16x8*)(pw + (pbuf) * 16384) = po0; *(bf16x8*)(pw + (pbuf) * 16384 + 16) = po1; } while (0)
; template <int PROBE, int MODE>
; DI void dattn_body(const u16* __restrict__ Qb, const u16* __restrict__ Kh, const u16* __restrict__ Vh, u16* __restrict__ Ob, const u16* __restrict__ O1, float lam, const float* __restrict__ subg, int seq, int q0, float kmax2, char* lds) {
;     ...
;   const float biasL = __uint_as_float(__builtin_amdgcn_readfirstlane(__float_as_uint(tab[0]))), biasR = __uint_as_float(__builtin_amdgcn_readfirstlane(__float_as_uint(tab[256])));
;   const float Mrow = C * __builtin_sqrtf(q2 * kmax2) + tab[257];
;   QKH(0);
;   { SMX_SETUP(0) SMX_CH(0); SMX_CH(1); SMX_CH(2); SMX_CH(3); SMX_FIN(0); }
	ds_read_b32 v2, v2
	v_readlane_b32 s0, v255, 10
	v_mul_f32_e32 v1, 0x4f800000, v0
	s_add_i32 s35, s87, 0xff
	s_cmpk_gt_u32 s35, 0x1be
	s_waitcnt lgkmcnt(0)
	v_readfirstlane_b32 s20, v2
	v_mov_b32_e32 v2, s0
	s_mov_b32 s0, 0xf800000
	v_cmp_gt_f32_e32 vcc, s0, v0
	ds_read_b64 v[18:19], v2
	s_waitcnt lgkmcnt(0)
	v_readfirstlane_b32 s21, v18
	v_cndmask_b32_e32 v0, v0, v1, vcc
	v_sqrt_f32_e32 v1, v0
	v_mov_b32_e32 v158, v19
	v_add_u32_e32 v2, -1, v1
	v_fma_f32 v3, -v2, v1, v0
	v_cmp_ge_f32_e64 s[0:1], 0, v3
	v_add_u32_e32 v3, 1, v1
	s_nop 0
	v_cndmask_b32_e64 v2, v1, v2, s[0:1]
	v_fma_f32 v1, -v3, v1, v0
	v_cmp_lt_f32_e64 s[0:1], 0, v1
	s_nop 1
	v_cndmask_b32_e64 v1, v2, v3, s[0:1]
	v_mul_f32_e32 v2, 0x37800000, v1
	v_cndmask_b32_e32 v1, v1, v2, vcc
	v_cmp_class_f32_e32 vcc, v0, v219
	s_movk_i32 s0, 0x70
	v_bitop3_b32 v198, v16, v195, s0 bitop3:0x78
	v_cndmask_b32_e32 v18, v1, v0, vcc
	v_lshlrev_b32_e32 v0, 13, v196
	v_lshlrev_b32_e32 v1, 8, v192
	v_add3_u32 v21, s95, v0, v1
	v_add_u32_e32 v0, v21, v198
	ds_read_b128 v[0:3], v0
	v_add_u32_e32 v23, v21, v199
	ds_read_b128 v[26:29], v23
	s_waitcnt lgkmcnt(1)
	v_mfma_f32_32x32x16_bf16 v[0:15], v[0:3], v[82:85], 0
	v_add_u32_e32 v23, v21, v200
	s_movk_i32 s0, 0x60
	v_bitop3_b32 v201, v16, v20, s0 bitop3:0x36
	s_movk_i32 s0, 0xa0
	v_bitop3_b32 v203, v16, v20, s0 bitop3:0x36
	s_movk_i32 s0, 0xc0
	v_bitop3_b32 v204, v16, v20, s0 bitop3:0x36
	s_waitcnt lgkmcnt(0)
	v_mfma_f32_32x32x16_bf16 v[0:15], v[26:29], v[86:89], v[0:15]
	ds_read_b128 v[26:29], v23
	v_add_u32_e32 v23, v21, v201
	s_movk_i32 s0, 0xe0
	v_bitop3_b32 v205, v16, v20, s0 bitop3:0x36
	v_add_u32_e32 v16, v21, v205
	s_cselect_b64 s[0:1], -1, 0
	s_cmp_lt_i32 s18, 0
	s_waitcnt lgkmcnt(0)
	v_mfma_f32_32x32x16_bf16 v[0:15], v[26:29], v[90:93], v[0:15]
	ds_read_b128 v[26:29], v23
	v_add_u32_e32 v23, v21, v202
	v_fmac_f32_e32 v158, 0x3e0293ee, v18
	s_cselect_b64 s[44:45], -1, 0
	v_mov_b32_e32 v18, s21
	s_cmpk_lt_u32 s35, 0x1bf
	s_mov_b64 s[18:19], -1
	s_waitcnt lgkmcnt(0)
	v_mfma_f32_32x32x16_bf16 v[0:15], v[26:29], v[94:97], v[0:15]
	ds_read_b128 v[26:29], v23
	v_add_u32_e32 v23, v21, v203
	s_waitcnt lgkmcnt(0)
	v_mfma_f32_32x32x16_bf16 v[0:15], v[26:29], v[98:101], v[0:15]
	ds_read_b128 v[26:29], v23
	v_add_u32_e32 v23, v21, v204
	s_waitcnt lgkmcnt(0)
	v_mfma_f32_32x32x16_bf16 v[0:15], v[26:29], v[102:105], v[0:15]
	ds_read_b128 v[26:29], v23
	s_waitcnt lgkmcnt(0)
	v_mfma_f32_32x32x16_bf16 v[0:15], v[26:29], v[106:109], v[0:15]
	ds_read_b128 v[26:29], v16
	v_mov_b32_e32 v16, s20
	v_cndmask_b32_e64 v16, v16, v18, s[44:45]
	v_sub_f32_e32 v16, v16, v158
	s_waitcnt lgkmcnt(0)
	v_mfma_f32_32x32x16_bf16 v[0:15], v[26:29], v[110:113], v[0:15]
	s_cbranch_scc1 .LBB0_231
	s_nop 10
	v_pk_fma_f32 v[18:19], v[0:1], s[12:13], v[16:17] op_sel_hi:[1,0,0]
	v_pk_fma_f32 v[20:21], v[2:3], s[12:13], v[16:17] op_sel_hi:[1,0,0]
	s_mov_b64 s[18:19], 0

; #define KDMA(k0, b) do { const char* g_ = (const char*)(Kh + (long)(k0) * DM); char* l_ = K_lds + (b) * 16384 + wu * 1024; \
;     DMA16(g_ + koff[0], l_); DMA16(g_ + koff[1], l_ + 8192); } while (0)
; #define VDMA(k0, b) do { const char* g_ = (const char*)(Vh + (long)(k0) * DM); char* l_ = V_lds + (b) * 32768 + wu * 1024; \
;     DMA16(g_ + voff[0], l_); DMA16(g_ + voff[1], l_ + 8192); DMA16(g_ + voff[0] + 256, l_ + 16384); DMA16(g_ + voff[1] + 256, l_ + 16384 + 8192); } while (0)
; #define DMAWAIT() asm volatile("s_waitcnt vmcnt(0)" ::: "memory")
; #define QKH(b) do { S = f32x16{}; const char* Ks_ = K_lds + (b) * 16384; _Pragma("unroll") for (int d0 = 0; d0 < 8; ++d0) { \
;     const bf16x8 kf = *reinterpret_cast<const bf16x8*>(Ks_ + KSWZ(32 * kh + r32, (d0 * 16 + hi * 8) * 2)); \
;     S = __builtin_amdgcn_mfma_f32_32x32x16_bf16(kf, qr[d0], S, 0, 0, 0); } } while (0)
; #define SMX_FIN(pbuf) do { _Pragma("unroll") for (int r = 0; r < 16; ++r) l_reg += S[r]; \
;     PK4S(0, po0); PK4S(8, po1); \
;     *(bf16x8*)(pw + (pbuf) * 16384) = po0; *(bf16x8*)(pw + (pbuf) * 16384 + 16) = po1; } while (0)
; template <int PROBE, int MODE>
; DI void dattn_body(const u16* __restrict__ Qb, const u16* __restrict__ Kh, const u16* __restrict__ Vh, u16* __restrict__ Ob, const u16* __restrict__ O1, float lam, const float* __restrict__ subg, int seq, int q0, float kmax2, char* lds) {
;     ...
;   f32x16 o[4] = {}; f32x16 S; float l_reg = 0.f; bf16x8 po0, po1; const int NT = seq / KVBLK;
;   KDMA(0, 0); VDMA(0, 0); KDMA(KVBLK, 1);
;   DMAWAIT();
;   __syncthreads();
;   const float biasL = __uint_as_float(__builtin_amdgcn_readfirstlane(__float_as_uint(tab[0]))), biasR = __uint_as_float(__builtin_amdgcn_readfirstlane(__float_as_uint(tab[256])));
;   const float Mrow = C * __builtin_sqrtf(q2 * kmax2) + tab[257];
;   QKH(0);
;   { SMX_SETUP(0) SMX_CH(0); SMX_CH(1); SMX_CH(2); SMX_CH(3); SMX_FIN(0); }
;   __syncthreads();
.LBB0_245:
	v_lshlrev_b32_e32 v14, 11, v194
	v_lshlrev_b32_e32 v15, 5, v193
	s_add_i32 s40, 16, 0x18000
	v_add3_u32 v211, s40, v14, v15
	v_add_f32_e32 v14, 0, v18
	v_add_f32_e32 v14, v19, v14
	v_add_f32_e32 v14, v20, v14
	v_add_f32_e32 v14, v21, v14
	v_exp_f32_e32 v12, v0
	v_cvt_pk_bf16_f32 v114, v18, v19
	v_cvt_pk_bf16_f32 v115, v20, v21
	v_cvt_pk_bf16_f32 v116, v8, v9
	v_add_f32_e32 v8, v8, v14
	v_exp_f32_e32 v1, v1
	v_add_f32_e32 v8, v9, v8
	v_exp_f32_e32 v4, v4
	v_add_f32_e32 v8, v10, v8
	v_exp_f32_e32 v5, v5
	v_add_f32_e32 v8, v11, v8
	v_exp_f32_e32 v2, v2
	v_add_f32_e32 v8, v12, v8
	v_exp_f32_e32 v3, v3
	v_cvt_pk_bf16_f32 v117, v10, v11
	v_cvt_pk_bf16_f32 v130, v12, v1
	v_add_f32_e32 v1, v1, v8
	v_exp_f32_e32 v6, v6
	v_add_f32_e32 v1, v4, v1
	v_exp_f32_e32 v7, v7
	v_add_f32_e32 v1, v5, v1
	v_xor_b32_e32 v208, 1, v194
	v_add_f32_e32 v1, v2, v1
	v_lshlrev_b32_e32 v0, 3, v193
	v_lshlrev_b32_e32 v16, 11, v208
	v_add_f32_e32 v1, v3, v1
	s_lshl_b64 s[0:1], s[46:47], 11
	s_lshl_b32 s24, s33, 8
	v_lshlrev_b32_e32 v13, 1, v193
	v_add3_u32 v210, s40, v16, v15
	v_and_b32_e32 v16, 24, v0
	s_add_i32 s33, s87, 0xffffff80
	v_add_f32_e32 v1, v6, v1
	s_movk_i32 s18, 0xc0
	v_and_b32_e32 v13, 32, v13
	v_and_b32_e32 v22, 0x100, v0
	v_add_f32_e32 v209, v7, v1
	v_and_or_b32 v1, v17, s18, v16
	s_cmp_lg_u32 16, -1
	v_lshlrev_b32_e32 v23, 14, v196
	v_or3_b32 v1, v1, v13, v22
	s_cselect_b32 s18, 16, 0
	v_add3_u32 v212, v23, s18, v1
	v_readlane_b32 s18, v255, 38
	s_mul_i32 s79, s18, s41
	v_cvt_pk_bf16_f32 v131, v4, v5
	v_cvt_pk_bf16_f32 v132, v2, v3
	v_or_b32_e32 v2, v25, v192
	v_add_u32_e32 v1, s79, v25
	v_lshl_add_u32 v213, v2, 8, s95
	v_add_u32_e32 v2, v1, v206
	v_add_u32_e32 v1, v1, v207
	v_sub_u32_e32 v2, v2, v192
	v_sub_u32_e32 v1, v1, v192
	v_cvt_pk_bf16_f32 v133, v6, v7
	v_mov_b32_e32 v0, 0
	v_sub_u32_e32 v2, v2, v197
	s_lshl_b32 s41, s100, 7
	v_sub_u32_e32 v1, v1, v197
	v_mov_b32_e32 v153, v177
	v_mov_b32_e32 v155, v177
	v_mov_b32_e32 v159, v158
	v_permlane32_swap_b32_e32 v114, v116
	v_permlane32_swap_b32_e32 v115, v117
	v_permlane32_swap_b32_e32 v130, v132
	v_permlane32_swap_b32_e32 v131, v133
	s_mov_b32 s25, 0
	v_cmp_eq_u32_e64 s[46:47], 0, v196
	v_subrev_u32_e32 v214, s41, v2
	v_subrev_u32_e32 v215, s41, v1
	s_movk_i32 s18, 0x80
	s_mov_b32 s54, 0x8000
	s_mov_b32 s55, 0
	v_mov_b32_e32 v1, v0
	v_mov_b32_e32 v2, v0
	v_mov_b32_e32 v3, v0
	v_mov_b32_e32 v4, v0
	v_mov_b32_e32 v5, v0
	v_mov_b32_e32 v6, v0
	v_mov_b32_e32 v7, v0
	v_mov_b32_e32 v8, v0
	v_mov_b32_e32 v9, v0
	v_mov_b32_e32 v10, v0
	v_mov_b32_e32 v11, v0
	v_mov_b32_e32 v12, v0
	v_mov_b32_e32 v13, v0
	v_mov_b32_e32 v14, v0
	v_mov_b32_e32 v15, v0
	v_mov_b32_e32 v16, v0
	v_mov_b32_e32 v17, v0
	v_mov_b32_e32 v18, v0
	v_mov_b32_e32 v19, v0
	v_mov_b32_e32 v20, v0
	v_mov_b32_e32 v21, v0
	v_mov_b32_e32 v22, v0
	v_mov_b32_e32 v23, v0
	v_mov_b32_e32 v24, v0
	v_mov_b32_e32 v25, v0
	v_mov_b32_e32 v26, v0
	v_mov_b32_e32 v27, v0
	v_mov_b32_e32 v28, v0
	v_mov_b32_e32 v29, v0
	v_mov_b32_e32 v30, v0
	v_mov_b32_e32 v31, v0
	v_mov_b32_e32 v32, v0
	v_mov_b32_e32 v33, v0
	v_mov_b32_e32 v34, v0
	v_mov_b32_e32 v35, v0
	v_mov_b32_e32 v36, v0
	v_mov_b32_e32 v37, v0
	v_mov_b32_e32 v38, v0
	v_mov_b32_e32 v39, v0
	v_mov_b32_e32 v40, v0
	v_mov_b32_e32 v41, v0
	v_mov_b32_e32 v42, v0
	v_mov_b32_e32 v43, v0
	v_mov_b32_e32 v44, v0
	v_mov_b32_e32 v45, v0
	v_mov_b32_e32 v46, v0
	v_mov_b32_e32 v47, v0
	v_mov_b32_e32 v48, v0
	v_mov_b32_e32 v49, v0
	v_mov_b32_e32 v50, v0
	v_mov_b32_e32 v51, v0
	v_mov_b32_e32 v52, v0
	v_mov_b32_e32 v53, v0
	v_mov_b32_e32 v54, v0
	v_mov_b32_e32 v55, v0
	v_mov_b32_e32 v56, v0
	v_mov_b32_e32 v57, v0
	v_mov_b32_e32 v58, v0
	v_mov_b32_e32 v59, v0
	v_mov_b32_e32 v60, v0
	v_mov_b32_e32 v61, v0
	v_mov_b32_e32 v62, v0
	v_mov_b32_e32 v63, v0
	ds_write_b128 v211, v[114:117]
	ds_write_b128 v211, v[130:133] offset:16
	s_waitcnt lgkmcnt(0)
	s_barrier
	s_branch .LBB0_247

; #define SBAR() __builtin_amdgcn_sched_barrier(0)
; #define KDMA(k0, b) do { const char* g_ = (const char*)(Kh + (long)(k0) * DM); char* l_ = K_lds + (b) * 16384 + wu * 1024; \
;     DMA16(g_ + koff[0], l_); DMA16(g_ + koff[1], l_ + 8192); } while (0)
; #define VDMA(k0, b) do { const char* g_ = (const char*)(Vh + (long)(k0) * DM); char* l_ = V_lds + (b) * 32768 + wu * 1024; \
;     DMA16(g_ + voff[0], l_); DMA16(g_ + voff[1], l_ + 8192); DMA16(g_ + voff[0] + 256, l_ + 16384); DMA16(g_ + voff[1] + 256, l_ + 16384 + 8192); } while (0)
; #define VRD(D0, X) do { X##0 = tr_read<v_rd_off(D0, 0, 0)>(vb); X##1 = tr_read<v_rd_off(D0, 0, 1)>(vb); X##2 = tr_read<v_rd_off(D0, 1, 0)>(vb); X##3 = tr_read<v_rd_off(D0, 1, 1)>(vb); \
;     X##4 = tr_read<v_rd_off(D0, 2, 0)>(vb); X##5 = tr_read<v_rd_off(D0, 2, 1)>(vb); X##6 = tr_read<v_rd_off(D0, 3, 0)>(vb); X##7 = tr_read<v_rd_off(D0, 3, 1)>(vb); } while (0)
; template <int PROBE, int MODE>
; DI void dattn_body(const u16* __restrict__ Qb, const u16* __restrict__ Kh, const u16* __restrict__ Vh, u16* __restrict__ Ob, const u16* __restrict__ O1, float lam, const float* __restrict__ subg, int seq, int q0, float kmax2, char* lds) {
;     ...
;   for (int j = 0; j < NT; ++j) {
;     const bool more = j + 1 < NT;
;     if (!(PROBE & 1)) {
;       if (j + 2 < NT) KDMA((j + 2) * KVBLK, j & 1);
;       if (more) VDMA((j + 1) * KVBLK, (j + 1) & 1);
;     }
;     bf16x8 kf[8];
;     if (more) { const char* Ks_ = K_lds + ((j + 1) & 1) * 16384;
; #pragma unroll
;       for (int d0 = 0; d0 < 8; ++d0) kf[d0] = *reinterpret_cast<const bf16x8*>(Ks_ + KSWZ(32 * kh + r32, (d0 * 16 + hi * 8) * 2)); }
;     const bf16x8 pb0 = *(const bf16x8*)(pr + (j & 1) * 16384), pb1 = *(const bf16x8*)(pr + (j & 1) * 16384 + 16);
;     const int vb = vb0 + (j & 1) * 32768;
;     s16x4 va0, va1, va2, va3, va4, va5, va6, va7, vc0, vc1, vc2, vc3, vc4, vc5, vc6, vc7;
;     VRD(0, va);
;     if (more) { asm volatile("s_waitcnt lgkmcnt(10)" ::: "memory"); SBAR();
;       if (!(PROBE & 4)) { S = f32x16{};
; #pragma unroll
;       for (int d0 = 0; d0 < 8; ++d0) S = __builtin_amdgcn_mfma_f32_32x32x16_bf16(kf[d0], qr[d0], S, 0, 0, 0); }
;       SBAR(); }
.LBB0_247:
	s_add_i32 s100, s18, -1
	s_cmp_ge_i32 s100, s33
	s_cselect_b32 s100, 1, 0
	s_sub_i32 s101, s18, 64
	s_cmp_le_i32 s101, s35
	s_cselect_b32 s101, 1, 0
	s_and_b32 s100, s100, s101
	s_cbranch_scc0 .Lfast0
	s_sub_i32 s72, s18, 64
	s_and_b32 s101, s25, 0x4000
	s_addk_i32 s25, 0x4000
	s_and_b32 s19, s25, 0x4000
	v_add_u32_e32 v68, s19, v213
	v_add_u32_e32 v64, v68, v198
	v_add_u32_e32 v69, v68, v199
	ds_read_b128 v[64:67], v64
	ds_read_b128 v[118:121], v69
	v_add_u32_e32 v69, v68, v200
	v_add_u32_e32 v70, v68, v201
	ds_read_b128 v[122:125], v69
	ds_read_b128 v[126:129], v70
	v_add_u32_e32 v69, v68, v202
	v_add_u32_e32 v70, v68, v203
	ds_read_b128 v[134:137], v69
	ds_read_b128 v[138:141], v70
	v_add_u32_e32 v69, v68, v204
	v_add_u32_e32 v68, v68, v205
	s_and_b32 s48, s55, 1
	ds_read_b128 v[142:145], v69
	ds_read_b128 v[146:149], v68
	v_lshl_add_u32 v68, s48, 14, v210
	ds_read_b128 v[162:165], v68
	ds_read_b128 v[166:169], v68 offset:16
	v_lshl_add_u32 v216, s48, 15, v212
	s_lshl_b32 s48, s72, 12
	s_add_u32 s48, s16, s48
	s_addc_u32 s49, s17, 0
	s_add_u32 s74, s48, 0x100
	s_addc_u32 s75, s49, 0
	s_and_b32 s100, s54, 0x8000
	s_add_i32 s100, s85, s100
	s_waitcnt lgkmcnt(9)
	v_mfma_f32_32x32x16_bf16 v[64:79], v[64:67], v[82:85], 0
	ds_read_b64_tr_b16 v[234:235], v216 offset:0
	ds_read_b64_tr_b16 v[236:237], v216 offset:0x800
	s_waitcnt lgkmcnt(10)
	v_mfma_f32_32x32x16_bf16 v[64:79], v[118:121], v[86:89], v[64:79]
	ds_read_b64_tr_b16 v[238:239], v216 offset:0x1000
	ds_read_b64_tr_b16 v[240:241], v216 offset:0x1800
	s_waitcnt lgkmcnt(11)
	v_mfma_f32_32x32x16_bf16 v[64:79], v[122:125], v[90:93], v[64:79]
	ds_read_b64_tr_b16 v[242:243], v216 offset:0x2000
	ds_read_b64_tr_b16 v[244:245], v216 offset:0x2800
	s_waitcnt lgkmcnt(12)
	v_mfma_f32_32x32x16_bf16 v[64:79], v[126:129], v[94:97], v[64:79]
	ds_read_b64_tr_b16 v[246:247], v216 offset:0x3000
	ds_read_b64_tr_b16 v[248:249], v216 offset:0x3800
	s_mov_b32 m0, s100
	s_waitcnt lgkmcnt(13)
	v_mfma_f32_32x32x16_bf16 v[64:79], v[134:137], v[98:101], v[64:79]
	global_load_lds_dwordx4 v176, s[48:49]
	s_add_i32 m0, s100, 0x2000
	s_waitcnt lgkmcnt(12)
	v_mfma_f32_32x32x16_bf16 v[64:79], v[138:141], v[102:105], v[64:79]
	global_load_lds_dwordx4 v156, s[48:49]
	s_add_i32 m0, s100, 0x4000
	s_waitcnt lgkmcnt(11)
	v_mfma_f32_32x32x16_bf16 v[64:79], v[142:145], v[106:109], v[64:79]
	global_load_lds_dwordx4 v176, s[74:75]
	s_add_i32 m0, s100, 0x6000
	s_waitcnt lgkmcnt(10)
	v_mfma_f32_32x32x16_bf16 v[64:79], v[146:149], v[110:113], v[64:79]
	global_load_lds_dwordx4 v156, s[74:75]
	s_add_i32 s48, s55, 2
	s_cmp_ge_u32 s48, s11
	s_cbranch_scc1 .Lda0_k_done
	s_lshl_b32 s48, s18, 12
	s_add_u32 s48, s14, s48
	s_addc_u32 s49, s15, 0
	s_add_i32 s100, s82, s101
	s_mov_b32 m0, s100
	s_nop 0
	global_load_lds_dwordx4 v152, s[48:49]
	s_add_i32 m0, s100, 0x2000
	s_nop 0
	global_load_lds_dwordx4 v154, s[48:49]

; #define SBAR() __builtin_amdgcn_sched_barrier(0)
; #define KDMA(k0, b) do { const char* g_ = (const char*)(Kh + (long)(k0) * DM); char* l_ = K_lds + (b) * 16384 + wu * 1024; \
;     DMA16(g_ + koff[0], l_); DMA16(g_ + koff[1], l_ + 8192); } while (0)
; #define VDMA(k0, b) do { const char* g_ = (const char*)(Vh + (long)(k0) * DM); char* l_ = V_lds + (b) * 32768 + wu * 1024; \
;     DMA16(g_ + voff[0], l_); DMA16(g_ + voff[1], l_ + 8192); DMA16(g_ + voff[0] + 256, l_ + 16384); DMA16(g_ + voff[1] + 256, l_ + 16384 + 8192); } while (0)
; #define VRD(D0, X) do { X##0 = tr_read<v_rd_off(D0, 0, 0)>(vb); X##1 = tr_read<v_rd_off(D0, 0, 1)>(vb); X##2 = tr_read<v_rd_off(D0, 1, 0)>(vb); X##3 = tr_read<v_rd_off(D0, 1, 1)>(vb); \
;     X##4 = tr_read<v_rd_off(D0, 2, 0)>(vb); X##5 = tr_read<v_rd_off(D0, 2, 1)>(vb); X##6 = tr_read<v_rd_off(D0, 3, 0)>(vb); X##7 = tr_read<v_rd_off(D0, 3, 1)>(vb); } while (0)
; template <int PROBE, int MODE>
; DI void dattn_body(const u16* __restrict__ Qb, const u16* __restrict__ Kh, const u16* __restrict__ Vh, u16* __restrict__ Ob, const u16* __restrict__ O1, float lam, const float* __restrict__ subg, int seq, int q0, float kmax2, char* lds) {
;     ...
;   for (int j = 0; j < NT; ++j) {
;     const bool more = j + 1 < NT;
;     if (!(PROBE & 1)) {
;       if (j + 2 < NT) KDMA((j + 2) * KVBLK, j & 1);
;       if (more) VDMA((j + 1) * KVBLK, (j + 1) & 1);
;     }
;     bf16x8 kf[8];
;     if (more) { const char* Ks_ = K_lds + ((j + 1) & 1) * 16384;
; #pragma unroll
;       for (int d0 = 0; d0 < 8; ++d0) kf[d0] = *reinterpret_cast<const bf16x8*>(Ks_ + KSWZ(32 * kh + r32, (d0 * 16 + hi * 8) * 2)); }
;     const bf16x8 pb0 = *(const bf16x8*)(pr + (j & 1) * 16384), pb1 = *(const bf16x8*)(pr + (j & 1) * 16384 + 16);
;     const int vb = vb0 + (j & 1) * 32768;
;     s16x4 va0, va1, va2, va3, va4, va5, va6, va7, vc0, vc1, vc2, vc3, vc4, vc5, vc6, vc7;
;     VRD(0, va);
;     if (more) { asm volatile("s_waitcnt lgkmcnt(10)" ::: "memory"); SBAR();
;       if (!(PROBE & 4)) { S = f32x16{};
; #pragma unroll
;       for (int d0 = 0; d0 < 8; ++d0) S = __builtin_amdgcn_mfma_f32_32x32x16_bf16(kf[d0], qr[d0], S, 0, 0, 0); }
;       SBAR(); }
;     const bf16x8 A0 = kh ? pb0 : po0, A1 = kh ? pb1 : po1, A2 = kh ? po0 : pb0, A3 = kh ? po1 : pb1;
;     SMX_SETUP(j + 1)
.Lfast0:
	s_sub_i32 s72, s18, 64
	s_and_b32 s101, s25, 0x4000
	s_addk_i32 s25, 0x4000
	s_and_b32 s19, s25, 0x4000
	s_and_b32 s48, s55, 1
	v_lshl_add_u32 v68, s48, 14, v210
	ds_read_b128 v[162:165], v68
	ds_read_b128 v[166:169], v68 offset:16
	v_add_u32_e32 v68, s19, v213
	v_add_u32_e32 v64, v68, v198
	v_add_u32_e32 v69, v68, v199
	ds_read_b128 v[64:67], v64
	ds_read_b128 v[118:121], v69
	v_add_u32_e32 v69, v68, v200
	v_add_u32_e32 v70, v68, v201
	ds_read_b128 v[122:125], v69
	ds_read_b128 v[126:129], v70
	v_add_u32_e32 v69, v68, v202
	v_add_u32_e32 v70, v68, v203
	ds_read_b128 v[134:137], v69
	ds_read_b128 v[138:141], v70
	v_add_u32_e32 v69, v68, v204
	v_add_u32_e32 v68, v68, v205
	ds_read_b128 v[142:145], v69
	ds_read_b128 v[146:149], v68
	v_lshl_add_u32 v216, s48, 15, v212
	s_cmp_gt_i32 s72, s87
	s_cselect_b32 s100, s21, s20
	v_sub_f32_e32 v160, s100, v158
	s_lshl_b32 s48, s72, 12
	s_add_u32 s48, s16, s48
	s_addc_u32 s49, s17, 0
	s_add_u32 s74, s48, 0x100
	s_addc_u32 s75, s49, 0
	s_and_b32 s100, s54, 0x8000
	s_add_i32 s100, s85, s100
	s_waitcnt lgkmcnt(7)
	v_mfma_f32_32x32x16_bf16 v[64:79], v[64:67], v[82:85], 0
	ds_read_b64_tr_b16 v[234:235], v216 offset:0
	ds_read_b64_tr_b16 v[236:237], v216 offset:0x800
	s_waitcnt lgkmcnt(8)
	v_mfma_f32_32x32x16_bf16 v[64:79], v[118:121], v[86:89], v[64:79]
	ds_read_b64_tr_b16 v[238:239], v216 offset:0x1000
	ds_read_b64_tr_b16 v[240:241], v216 offset:0x1800
	v_cndmask_b32_e64 v119, v163, v115, s[46:47]
	v_cndmask_b32_e64 v118, v162, v114, s[46:47]
	v_cndmask_b32_e64 v121, v165, v117, s[46:47]
	v_cndmask_b32_e64 v120, v164, v116, s[46:47]
	s_waitcnt lgkmcnt(9)
	v_mfma_f32_32x32x16_bf16 v[64:79], v[122:125], v[90:93], v[64:79]
	ds_read_b64_tr_b16 v[242:243], v216 offset:0x2000
	ds_read_b64_tr_b16 v[244:245], v216 offset:0x2800
	v_cndmask_b32_e64 v123, v167, v131, s[46:47]
	v_cndmask_b32_e64 v122, v166, v130, s[46:47]
	v_cndmask_b32_e64 v125, v169, v133, s[46:47]
	v_cndmask_b32_e64 v124, v168, v132, s[46:47]
	s_waitcnt lgkmcnt(10)
	v_mfma_f32_32x32x16_bf16 v[64:79], v[126:129], v[94:97], v[64:79]
	ds_read_b64_tr_b16 v[246:247], v216 offset:0x3000
	ds_read_b64_tr_b16 v[248:249], v216 offset:0x3800
	v_cndmask_b32_e64 v127, v115, v163, s[46:47]
	v_cndmask_b32_e64 v126, v114, v162, s[46:47]
	v_cndmask_b32_e64 v129, v117, v165, s[46:47]
	v_cndmask_b32_e64 v128, v116, v164, s[46:47]
	s_mov_b32 m0, s100
	s_waitcnt lgkmcnt(11)
	v_mfma_f32_32x32x16_bf16 v[64:79], v[134:137], v[98:101], v[64:79]
	global_load_lds_dwordx4 v176, s[48:49]
	v_cndmask_b32_e64 v115, v131, v167, s[46:47]
	v_cndmask_b32_e64 v114, v130, v166, s[46:47]
	v_cndmask_b32_e64 v117, v133, v169, s[46:47]
	v_cndmask_b32_e64 v116, v132, v168, s[46:47]
	s_add_i32 m0, s100, 0x2000
	s_waitcnt lgkmcnt(10)
	v_mfma_f32_32x32x16_bf16 v[64:79], v[138:141], v[102:105], v[64:79]
	global_load_lds_dwordx4 v156, s[48:49]
	s_add_i32 m0, s100, 0x4000
	s_waitcnt lgkmcnt(9)
	v_mfma_f32_32x32x16_bf16 v[64:79], v[142:145], v[106:109], v[64:79]
	global_load_lds_dwordx4 v176, s[74:75]
	s_add_i32 m0, s100, 0x6000
	s_waitcnt lgkmcnt(8)
	v_mfma_f32_32x32x16_bf16 v[64:79], v[146:149], v[110:113], v[64:79]
	global_load_lds_dwordx4 v156, s[74:75]
	s_add_i32 s48, s55, 2
	s_cmp_ge_u32 s48, s11
	s_cbranch_scc1 .Lfast0_k_done
	s_lshl_b32 s48, s18, 12
	s_add_u32 s48, s14, s48
	s_addc_u32 s49, s15, 0
	s_add_i32 s100, s82, s101
	s_mov_b32 m0, s100
	s_nop 0
	global_load_lds_dwordx4 v152, s[48:49]
	s_add_i32 m0, s100, 0x2000
	s_nop 0
	global_load_lds_dwordx4 v154, s[48:49]
; #define DMAWAIT() asm volatile("s_waitcnt vmcnt(0)" ::: "memory")
; #define SMX_FIN(pbuf) do { _Pragma("unroll") for (int r = 0; r < 16; ++r) l_reg += S[r]; \
;     PK4S(0, po0); PK4S(8, po1); \
;     *(bf16x8*)(pw + (pbuf) * 16384) = po0; *(bf16x8*)(pw + (pbuf) * 16384 + 16) = po1; } while (0)
; #define VRD(D0, X) do { X##0 = tr_read<v_rd_off(D0, 0, 0)>(vb); X##1 = tr_read<v_rd_off(D0, 0, 1)>(vb); X##2 = tr_read<v_rd_off(D0, 1, 0)>(vb); X##3 = tr_read<v_rd_off(D0, 1, 1)>(vb); \
;     X##4 = tr_read<v_rd_off(D0, 2, 0)>(vb); X##5 = tr_read<v_rd_off(D0, 2, 1)>(vb); X##6 = tr_read<v_rd_off(D0, 3, 0)>(vb); X##7 = tr_read<v_rd_off(D0, 3, 1)>(vb); } while (0)
; #define LWAIT() do { asm volatile("s_waitcnt lgkmcnt(0)" ::: "memory"); SBAR(); } while (0)
; #define VMMP(D0, X) do { if (!(PROBE & 8)) VMM(D0, X); } while (0)
; #define SMXP(c) do { if (!(PROBE & 2)) { if (more) SMX_CH(c); } } while (0)
; template <int PROBE, int MODE>
; DI void dattn_body(const u16* __restrict__ Qb, const u16* __restrict__ Kh, const u16* __restrict__ Vh, u16* __restrict__ Ob, const u16* __restrict__ O1, float lam, const float* __restrict__ subg, int seq, int q0, float kmax2, char* lds) {
;     ...
;     LWAIT(); VRD(1, vc); VMMP(0, va); SMXP(0);
;     LWAIT(); VRD(2, va); VMMP(1, vc); SMXP(1);
;     LWAIT(); VRD(3, vc); VMMP(2, va); SMXP(2);
;     LWAIT(); VMMP(3, vc); SMXP(3);
;     if (!(PROBE & 2)) { if (more) SMX_FIN((j + 1) & 1); }
;     DMAWAIT();
;     __syncthreads();
.Lfast0_k_done:
	s_waitcnt lgkmcnt(6)
	v_mfma_f32_32x32x16_bf16 v[0:15], v[118:121], v[234:237], v[0:15]
	ds_read_b64_tr_b16 v[138:139], v216 offset:0x200
	ds_read_b64_tr_b16 v[140:141], v216 offset:0xa00
	s_waitcnt lgkmcnt(6)
	v_mfma_f32_32x32x16_bf16 v[0:15], v[122:125], v[238:241], v[0:15]
	ds_read_b64_tr_b16 v[142:143], v216 offset:0x1200
	ds_read_b64_tr_b16 v[144:145], v216 offset:0x1a00
	s_nop 1
	v_fma_f32 v162, v64, s12, v160
	v_fma_f32 v163, v65, s12, v160
	v_fma_f32 v164, v66, s12, v160
	v_fma_f32 v165, v67, s12, v160
	s_waitcnt lgkmcnt(6)
	v_mfma_f32_32x32x16_bf16 v[0:15], v[126:129], v[242:245], v[0:15]
	ds_read_b64_tr_b16 v[134:135], v216 offset:0x2200
	ds_read_b64_tr_b16 v[136:137], v216 offset:0x2a00
	v_fma_f32 v166, v68, s12, v160
	v_fma_f32 v167, v69, s12, v160
	v_exp_f32_e32 v162, v162
	v_exp_f32_e32 v163, v163
	s_waitcnt lgkmcnt(6)
	v_mfma_f32_32x32x16_bf16 v[0:15], v[114:117], v[246:249], v[0:15]
	ds_read_b64_tr_b16 v[130:131], v216 offset:0x3200
	ds_read_b64_tr_b16 v[132:133], v216 offset:0x3a00
	v_fma_f32 v168, v70, s12, v160
	v_fma_f32 v169, v71, s12, v160
	v_exp_f32_e32 v164, v164
	v_exp_f32_e32 v165, v165
	s_waitcnt lgkmcnt(6)
	v_mfma_f32_32x32x16_bf16 v[16:31], v[118:121], v[138:141], v[16:31]
	ds_read_b64_tr_b16 v[146:147], v216 offset:0x400
	ds_read_b64_tr_b16 v[148:149], v216 offset:0xc00
	v_exp_f32_e32 v166, v166
	v_exp_f32_e32 v167, v167
	v_add_f32_e32 v209, v162, v209
	v_add_f32_e32 v209, v163, v209
	s_waitcnt lgkmcnt(6)
	v_mfma_f32_32x32x16_bf16 v[16:31], v[122:125], v[142:145], v[16:31]
	ds_read_b64_tr_b16 v[142:143], v216 offset:0x1400
	ds_read_b64_tr_b16 v[144:145], v216 offset:0x1c00
	v_exp_f32_e32 v168, v168
	v_exp_f32_e32 v169, v169
	v_add_f32_e32 v209, v164, v209
	v_add_f32_e32 v209, v165, v209
	v_fma_f32 v244, v72, s12, v160
	v_fma_f32 v245, v73, s12, v160
	s_waitcnt lgkmcnt(6)
	v_mfma_f32_32x32x16_bf16 v[16:31], v[126:129], v[134:137], v[16:31]
	ds_read_b64_tr_b16 v[138:139], v216 offset:0x2400
	ds_read_b64_tr_b16 v[140:141], v216 offset:0x2c00
	v_fma_f32 v246, v74, s12, v160
	v_fma_f32 v247, v75, s12, v160
	v_add_f32_e32 v209, v166, v209
	v_add_f32_e32 v209, v167, v209
	s_waitcnt lgkmcnt(6)
	v_mfma_f32_32x32x16_bf16 v[16:31], v[114:117], v[130:133], v[16:31]
	ds_read_b64_tr_b16 v[64:65], v216 offset:0x3400
	ds_read_b64_tr_b16 v[66:67], v216 offset:0x3c00
	v_fma_f32 v76, v76, s12, v160
	v_fma_f32 v77, v77, s12, v160
	v_fma_f32 v78, v78, s12, v160
	v_fma_f32 v79, v79, s12, v160
	s_waitcnt lgkmcnt(6)
	v_mfma_f32_32x32x16_bf16 v[32:47], v[118:121], v[146:149], v[32:47]
	v_exp_f32_e32 v244, v244
	v_exp_f32_e32 v245, v245
	v_add_f32_e32 v209, v168, v209
	v_add_f32_e32 v209, v169, v209
	v_cvt_pk_bf16_f32 v236, v162, v163
	v_cvt_pk_bf16_f32 v237, v164, v165
	s_waitcnt lgkmcnt(4)
	v_mfma_f32_32x32x16_bf16 v[32:47], v[122:125], v[142:145], v[32:47]
	ds_read_b64_tr_b16 v[142:143], v216 offset:0x600
	ds_read_b64_tr_b16 v[144:145], v216 offset:0xe00
	ds_read_b64_tr_b16 v[130:131], v216 offset:0x1600
	ds_read_b64_tr_b16 v[132:133], v216 offset:0x1e00
	v_exp_f32_e32 v246, v246
	v_exp_f32_e32 v247, v247
	v_cvt_pk_bf16_f32 v238, v166, v167
	v_cvt_pk_bf16_f32 v239, v168, v169
	s_waitcnt lgkmcnt(6)
	v_mfma_f32_32x32x16_bf16 v[32:47], v[126:129], v[138:141], v[32:47]
	ds_read_b64_tr_b16 v[134:135], v216 offset:0x2600
	ds_read_b64_tr_b16 v[136:137], v216 offset:0x2e00
	v_exp_f32_e32 v76, v76
	v_exp_f32_e32 v77, v77
	v_add_f32_e32 v209, v244, v209
	v_add_f32_e32 v209, v245, v209
	v_permlane32_swap_b32_e32 v236, v238
	s_waitcnt lgkmcnt(6)
	v_mfma_f32_32x32x16_bf16 v[32:47], v[114:117], v[64:67], v[32:47]
	ds_read_b64_tr_b16 v[68:69], v216 offset:0x3600
	ds_read_b64_tr_b16 v[70:71], v216 offset:0x3e00
	v_exp_f32_e32 v78, v78
	v_exp_f32_e32 v79, v79
	v_add_f32_e32 v209, v246, v209
	v_add_f32_e32 v209, v247, v209
	v_permlane32_swap_b32_e32 v237, v239
	s_waitcnt lgkmcnt(6)
	v_mfma_f32_32x32x16_bf16 v[48:63], v[118:121], v[142:145], v[48:63]
	v_add_u32_e32 v64, s19, v211
	v_add_f32_e32 v209, v76, v209
	v_add_f32_e32 v209, v77, v209
	v_cvt_pk_bf16_f32 v240, v244, v245
	v_cvt_pk_bf16_f32 v241, v246, v247
	ds_write_b128 v64, v[236:239]
	s_waitcnt lgkmcnt(5)
	v_mfma_f32_32x32x16_bf16 v[48:63], v[122:125], v[130:133], v[48:63]
	v_add_f32_e32 v209, v78, v209
	v_add_f32_e32 v209, v79, v209
	v_cvt_pk_bf16_f32 v242, v76, v77
	v_cvt_pk_bf16_f32 v243, v78, v79
	s_waitcnt lgkmcnt(3)
	v_mfma_f32_32x32x16_bf16 v[48:63], v[126:129], v[134:137], v[48:63]
	v_permlane32_swap_b32_e32 v240, v242
	v_permlane32_swap_b32_e32 v241, v243
	s_waitcnt lgkmcnt(1)
	v_mfma_f32_32x32x16_bf16 v[48:63], v[114:117], v[68:71], v[48:63]
	ds_write_b128 v64, v[240:243] offset:16
	v_mov_b32_e32 v114, v236
	v_mov_b32_e32 v115, v237
	v_mov_b32_e32 v116, v238
	v_mov_b32_e32 v117, v239
	v_mov_b32_e32 v130, v240
	v_mov_b32_e32 v131, v241
	v_mov_b32_e32 v132, v242
	v_mov_b32_e32 v133, v243
	s_add_i32 s55, s55, 1
	s_add_i32 s18, s18, 64
	s_add_i32 s54, s54, 0x8000
	s_cmp_eq_u32 s83, s55
	s_waitcnt vmcnt(0) lgkmcnt(0)
	s_barrier
	s_cbranch_scc1 .LBB0_265
	s_branch .LBB0_247

; #define SBAR() __builtin_amdgcn_sched_barrier(0)
; #define KDMA(k0, b) do { const char* g_ = (const char*)(Kh + (long)(k0) * DM); char* l_ = K_lds + (b) * 16384 + wu * 1024; \
;     DMA16(g_ + koff[0], l_); DMA16(g_ + koff[1], l_ + 8192); } while (0)
; #define VDMA(k0, b) do { const char* g_ = (const char*)(Vh + (long)(k0) * DM); char* l_ = V_lds + (b) * 32768 + wu * 1024; \
;     DMA16(g_ + voff[0], l_); DMA16(g_ + voff[1], l_ + 8192); DMA16(g_ + voff[0] + 256, l_ + 16384); DMA16(g_ + voff[1] + 256, l_ + 16384 + 8192); } while (0)
; #define VRD(D0, X) do { X##0 = tr_read<v_rd_off(D0, 0, 0)>(vb); X##1 = tr_read<v_rd_off(D0, 0, 1)>(vb); X##2 = tr_read<v_rd_off(D0, 1, 0)>(vb); X##3 = tr_read<v_rd_off(D0, 1, 1)>(vb); \
;     X##4 = tr_read<v_rd_off(D0, 2, 0)>(vb); X##5 = tr_read<v_rd_off(D0, 2, 1)>(vb); X##6 = tr_read<v_rd_off(D0, 3, 0)>(vb); X##7 = tr_read<v_rd_off(D0, 3, 1)>(vb); } while (0)
; template <int PROBE, int MODE>
; DI void dattn_body(const u16* __restrict__ Qb, const u16* __restrict__ Kh, const u16* __restrict__ Vh, u16* __restrict__ Ob, const u16* __restrict__ O1, float lam, const float* __restrict__ subg, int seq, int q0, float kmax2, char* lds) {
;     ...
;   for (int j = 0; j < NT; ++j) {
;     const bool more = j + 1 < NT;
;     if (!(PROBE & 1)) {
;       if (j + 2 < NT) KDMA((j + 2) * KVBLK, j & 1);
;       if (more) VDMA((j + 1) * KVBLK, (j + 1) & 1);
;     }
;     bf16x8 kf[8];
;     if (more) { const char* Ks_ = K_lds + ((j + 1) & 1) * 16384;
; #pragma unroll
;       for (int d0 = 0; d0 < 8; ++d0) kf[d0] = *reinterpret_cast<const bf16x8*>(Ks_ + KSWZ(32 * kh + r32, (d0 * 16 + hi * 8) * 2)); }
;     const bf16x8 pb0 = *(const bf16x8*)(pr + (j & 1) * 16384), pb1 = *(const bf16x8*)(pr + (j & 1) * 16384 + 16);
;     const int vb = vb0 + (j & 1) * 32768;
;     s16x4 va0, va1, va2, va3, va4, va5, va6, va7, vc0, vc1, vc2, vc3, vc4, vc5, vc6, vc7;
;     VRD(0, va);
;     if (more) { asm volatile("s_waitcnt lgkmcnt(10)" ::: "memory"); SBAR();
;       if (!(PROBE & 4)) { S = f32x16{};
; #pragma unroll
;       for (int d0 = 0; d0 < 8; ++d0) S = __builtin_amdgcn_mfma_f32_32x32x16_bf16(kf[d0], qr[d0], S, 0, 0, 0); }
;       SBAR(); }
.LBB0_285:
	s_add_i32 s100, s0, -1
	s_cmp_ge_i32 s100, s33
	s_cselect_b32 s100, 1, 0
	s_sub_i32 s101, s0, 64
	s_cmp_le_i32 s101, s35
	s_cselect_b32 s101, 1, 0
	s_and_b32 s100, s100, s101
	s_cbranch_scc0 .Lfast1
	s_sub_i32 s72, s0, 64
	s_and_b32 s101, s24, 0x4000
	s_addk_i32 s24, 0x4000
	s_and_b32 s1, s24, 0x4000
	v_add_u32_e32 v68, s1, v212
	v_add_u32_e32 v64, v68, v196
	v_add_u32_e32 v69, v68, v198
	ds_read_b128 v[64:67], v64
	ds_read_b128 v[118:121], v69
	v_add_u32_e32 v69, v68, v199
	v_add_u32_e32 v70, v68, v200
	ds_read_b128 v[122:125], v69
	ds_read_b128 v[126:129], v70
	v_add_u32_e32 v69, v68, v201
	v_add_u32_e32 v70, v68, v202
	ds_read_b128 v[134:137], v69
	ds_read_b128 v[138:141], v70
	v_add_u32_e32 v69, v68, v203
	v_add_u32_e32 v68, v68, v204
	s_and_b32 s4, s40, 1
	ds_read_b128 v[142:145], v69
	ds_read_b128 v[146:149], v68
	v_lshl_add_u32 v68, s4, 14, v209
	ds_read_b128 v[162:165], v68
	ds_read_b128 v[166:169], v68 offset:16
	v_lshl_add_u32 v215, s4, 15, v211
	s_lshl_b32 s4, s72, 12
	s_add_u32 s4, s16, s4
	s_addc_u32 s5, s17, 0
	s_add_u32 s18, s4, 0x100
	s_addc_u32 s19, s5, 0
	s_and_b32 s100, s25, 0x8000
	s_add_i32 s100, s39, s100
	s_waitcnt lgkmcnt(9)
	v_mfma_f32_32x32x16_bf16 v[64:79], v[64:67], v[82:85], 0
	ds_read_b64_tr_b16 v[234:235], v215 offset:0
	ds_read_b64_tr_b16 v[236:237], v215 offset:0x800
	s_waitcnt lgkmcnt(10)
	v_mfma_f32_32x32x16_bf16 v[64:79], v[118:121], v[86:89], v[64:79]
	ds_read_b64_tr_b16 v[238:239], v215 offset:0x1000
	ds_read_b64_tr_b16 v[240:241], v215 offset:0x1800
	s_waitcnt lgkmcnt(11)
	v_mfma_f32_32x32x16_bf16 v[64:79], v[122:125], v[90:93], v[64:79]
	ds_read_b64_tr_b16 v[242:243], v215 offset:0x2000
	ds_read_b64_tr_b16 v[244:245], v215 offset:0x2800
	s_waitcnt lgkmcnt(12)
	v_mfma_f32_32x32x16_bf16 v[64:79], v[126:129], v[94:97], v[64:79]
	ds_read_b64_tr_b16 v[246:247], v215 offset:0x3000
	ds_read_b64_tr_b16 v[248:249], v215 offset:0x3800
	s_mov_b32 m0, s100
	s_waitcnt lgkmcnt(13)
	v_mfma_f32_32x32x16_bf16 v[64:79], v[134:137], v[98:101], v[64:79]
	global_load_lds_dwordx4 v152, s[4:5]
	s_add_i32 m0, s100, 0x2000
	s_waitcnt lgkmcnt(12)
	v_mfma_f32_32x32x16_bf16 v[64:79], v[138:141], v[102:105], v[64:79]
	global_load_lds_dwordx4 v156, s[4:5]
	s_add_i32 m0, s100, 0x4000
	s_waitcnt lgkmcnt(11)
	v_mfma_f32_32x32x16_bf16 v[64:79], v[142:145], v[106:109], v[64:79]
	global_load_lds_dwordx4 v152, s[18:19]
	s_add_i32 m0, s100, 0x6000
	s_waitcnt lgkmcnt(10)
	v_mfma_f32_32x32x16_bf16 v[64:79], v[146:149], v[110:113], v[64:79]
	global_load_lds_dwordx4 v156, s[18:19]
	s_add_i32 s4, s40, 2
	s_cmp_ge_u32 s4, s11
	s_cbranch_scc1 .Lda1_k_done
	s_lshl_b32 s4, s0, 12
	s_add_u32 s4, s14, s4
	s_addc_u32 s5, s15, 0
	s_add_u32 s4, s4, 0x100
	s_addc_u32 s5, s5, 0
	s_add_i32 s100, s38, s101
	s_mov_b32 m0, s100
	s_nop 0
	global_load_lds_dwordx4 v176, s[4:5]
	s_add_i32 m0, s100, 0x2000
	s_nop 0
	global_load_lds_dwordx4 v154, s[4:5]

; #define SBAR() __builtin_amdgcn_sched_barrier(0)
; #define KDMA(k0, b) do { const char* g_ = (const char*)(Kh + (long)(k0) * DM); char* l_ = K_lds + (b) * 16384 + wu * 1024; \
;     DMA16(g_ + koff[0], l_); DMA16(g_ + koff[1], l_ + 8192); } while (0)
; #define VDMA(k0, b) do { const char* g_ = (const char*)(Vh + (long)(k0) * DM); char* l_ = V_lds + (b) * 32768 + wu * 1024; \
;     DMA16(g_ + voff[0], l_); DMA16(g_ + voff[1], l_ + 8192); DMA16(g_ + voff[0] + 256, l_ + 16384); DMA16(g_ + voff[1] + 256, l_ + 16384 + 8192); } while (0)
; #define VRD(D0, X) do { X##0 = tr_read<v_rd_off(D0, 0, 0)>(vb); X##1 = tr_read<v_rd_off(D0, 0, 1)>(vb); X##2 = tr_read<v_rd_off(D0, 1, 0)>(vb); X##3 = tr_read<v_rd_off(D0, 1, 1)>(vb); \
;     X##4 = tr_read<v_rd_off(D0, 2, 0)>(vb); X##5 = tr_read<v_rd_off(D0, 2, 1)>(vb); X##6 = tr_read<v_rd_off(D0, 3, 0)>(vb); X##7 = tr_read<v_rd_off(D0, 3, 1)>(vb); } while (0)
; template <int PROBE, int MODE>
; DI void dattn_body(const u16* __restrict__ Qb, const u16* __restrict__ Kh, const u16* __restrict__ Vh, u16* __restrict__ Ob, const u16* __restrict__ O1, float lam, const float* __restrict__ subg, int seq, int q0, float kmax2, char* lds) {
;     ...
;   for (int j = 0; j < NT; ++j) {
;     const bool more = j + 1 < NT;
;     if (!(PROBE & 1)) {
;       if (j + 2 < NT) KDMA((j + 2) * KVBLK, j & 1);
;       if (more) VDMA((j + 1) * KVBLK, (j + 1) & 1);
;     }
;     bf16x8 kf[8];
;     if (more) { const char* Ks_ = K_lds + ((j + 1) & 1) * 16384;
; #pragma unroll
;       for (int d0 = 0; d0 < 8; ++d0) kf[d0] = *reinterpret_cast<const bf16x8*>(Ks_ + KSWZ(32 * kh + r32, (d0 * 16 + hi * 8) * 2)); }
;     const bf16x8 pb0 = *(const bf16x8*)(pr + (j & 1) * 16384), pb1 = *(const bf16x8*)(pr + (j & 1) * 16384 + 16);
;     const int vb = vb0 + (j & 1) * 32768;
;     s16x4 va0, va1, va2, va3, va4, va5, va6, va7, vc0, vc1, vc2, vc3, vc4, vc5, vc6, vc7;
;     VRD(0, va);
;     if (more) { asm volatile("s_waitcnt lgkmcnt(10)" ::: "memory"); SBAR();
;       if (!(PROBE & 4)) { S = f32x16{};
; #pragma unroll
;       for (int d0 = 0; d0 < 8; ++d0) S = __builtin_amdgcn_mfma_f32_32x32x16_bf16(kf[d0], qr[d0], S, 0, 0, 0); }
;       SBAR(); }
;     const bf16x8 A0 = kh ? pb0 : po0, A1 = kh ? pb1 : po1, A2 = kh ? po0 : pb0, A3 = kh ? po1 : pb1;
;     SMX_SETUP(j + 1)
.Lfast1:
	s_sub_i32 s72, s0, 64
	s_and_b32 s101, s24, 0x4000
	s_addk_i32 s24, 0x4000
	s_and_b32 s1, s24, 0x4000
	s_and_b32 s4, s40, 1
	v_lshl_add_u32 v68, s4, 14, v209
	ds_read_b128 v[162:165], v68
	ds_read_b128 v[166:169], v68 offset:16
	v_add_u32_e32 v68, s1, v212
	v_add_u32_e32 v64, v68, v196
	v_add_u32_e32 v69, v68, v198
	ds_read_b128 v[64:67], v64
	ds_read_b128 v[118:121], v69
	v_add_u32_e32 v69, v68, v199
	v_add_u32_e32 v70, v68, v200
	ds_read_b128 v[122:125], v69
	ds_read_b128 v[126:129], v70
	v_add_u32_e32 v69, v68, v201
	v_add_u32_e32 v70, v68, v202
	ds_read_b128 v[134:137], v69
	ds_read_b128 v[138:141], v70
	v_add_u32_e32 v69, v68, v203
	v_add_u32_e32 v68, v68, v204
	ds_read_b128 v[142:145], v69
	ds_read_b128 v[146:149], v68
	v_lshl_add_u32 v215, s4, 15, v211
	s_cmp_gt_i32 s72, s87
	s_cselect_b32 s100, s21, s20
	v_sub_f32_e32 v160, s100, v158
	s_lshl_b32 s4, s72, 12
	s_add_u32 s4, s16, s4
	s_addc_u32 s5, s17, 0
	s_add_u32 s18, s4, 0x100
	s_addc_u32 s19, s5, 0
	s_and_b32 s100, s25, 0x8000
	s_add_i32 s100, s39, s100
	s_waitcnt lgkmcnt(7)
	v_mfma_f32_32x32x16_bf16 v[64:79], v[64:67], v[82:85], 0
	ds_read_b64_tr_b16 v[234:235], v215 offset:0
	ds_read_b64_tr_b16 v[236:237], v215 offset:0x800
	s_waitcnt lgkmcnt(8)
	v_mfma_f32_32x32x16_bf16 v[64:79], v[118:121], v[86:89], v[64:79]
	ds_read_b64_tr_b16 v[238:239], v215 offset:0x1000
	ds_read_b64_tr_b16 v[240:241], v215 offset:0x1800
	v_cndmask_b32_e64 v119, v163, v115, s[42:43]
	v_cndmask_b32_e64 v118, v162, v114, s[42:43]
	v_cndmask_b32_e64 v121, v165, v117, s[42:43]
	v_cndmask_b32_e64 v120, v164, v116, s[42:43]
	s_waitcnt lgkmcnt(9)
	v_mfma_f32_32x32x16_bf16 v[64:79], v[122:125], v[90:93], v[64:79]
	ds_read_b64_tr_b16 v[242:243], v215 offset:0x2000
	ds_read_b64_tr_b16 v[244:245], v215 offset:0x2800
	v_cndmask_b32_e64 v123, v167, v131, s[42:43]
	v_cndmask_b32_e64 v122, v166, v130, s[42:43]
	v_cndmask_b32_e64 v125, v169, v133, s[42:43]
	v_cndmask_b32_e64 v124, v168, v132, s[42:43]
	s_waitcnt lgkmcnt(10)
	v_mfma_f32_32x32x16_bf16 v[64:79], v[126:129], v[94:97], v[64:79]
	ds_read_b64_tr_b16 v[246:247], v215 offset:0x3000
	ds_read_b64_tr_b16 v[248:249], v215 offset:0x3800
	v_cndmask_b32_e64 v127, v115, v163, s[42:43]
	v_cndmask_b32_e64 v126, v114, v162, s[42:43]
	v_cndmask_b32_e64 v129, v117, v165, s[42:43]
	v_cndmask_b32_e64 v128, v116, v164, s[42:43]
	s_mov_b32 m0, s100
	s_waitcnt lgkmcnt(11)
	v_mfma_f32_32x32x16_bf16 v[64:79], v[134:137], v[98:101], v[64:79]
	global_load_lds_dwordx4 v152, s[4:5]
	v_cndmask_b32_e64 v115, v131, v167, s[42:43]
	v_cndmask_b32_e64 v114, v130, v166, s[42:43]
	v_cndmask_b32_e64 v117, v133, v169, s[42:43]
	v_cndmask_b32_e64 v116, v132, v168, s[42:43]
	s_add_i32 m0, s100, 0x2000
	s_waitcnt lgkmcnt(10)
	v_mfma_f32_32x32x16_bf16 v[64:79], v[138:141], v[102:105], v[64:79]
	global_load_lds_dwordx4 v156, s[4:5]
	s_add_i32 m0, s100, 0x4000
	s_waitcnt lgkmcnt(9)
	v_mfma_f32_32x32x16_bf16 v[64:79], v[142:145], v[106:109], v[64:79]
	global_load_lds_dwordx4 v152, s[18:19]
	s_add_i32 m0, s100, 0x6000
	s_waitcnt lgkmcnt(8)
	v_mfma_f32_32x32x16_bf16 v[64:79], v[146:149], v[110:113], v[64:79]
	global_load_lds_dwordx4 v156, s[18:19]
	s_add_i32 s4, s40, 2
	s_cmp_ge_u32 s4, s11
	s_cbranch_scc1 .Lfast1_k_done
	s_lshl_b32 s4, s0, 12
	s_add_u32 s4, s14, s4
	s_addc_u32 s5, s15, 0
	s_add_u32 s4, s4, 0x100
	s_addc_u32 s5, s5, 0
	s_add_i32 s100, s38, s101
	s_mov_b32 m0, s100
	s_nop 0
	global_load_lds_dwordx4 v176, s[4:5]
	s_add_i32 m0, s100, 0x2000
	s_nop 0
	global_load_lds_dwordx4 v154, s[4:5]
; #define DMAWAIT() asm volatile("s_waitcnt vmcnt(0)" ::: "memory")
; #define SMX_FIN(pbuf) do { _Pragma("unroll") for (int r = 0; r < 16; ++r) l_reg += S[r]; \
;     PK4S(0, po0); PK4S(8, po1); \
;     *(bf16x8*)(pw + (pbuf) * 16384) = po0; *(bf16x8*)(pw + (pbuf) * 16384 + 16) = po1; } while (0)
; #define VRD(D0, X) do { X##0 = tr_read<v_rd_off(D0, 0, 0)>(vb); X##1 = tr_read<v_rd_off(D0, 0, 1)>(vb); X##2 = tr_read<v_rd_off(D0, 1, 0)>(vb); X##3 = tr_read<v_rd_off(D0, 1, 1)>(vb); \
;     X##4 = tr_read<v_rd_off(D0, 2, 0)>(vb); X##5 = tr_read<v_rd_off(D0, 2, 1)>(vb); X##6 = tr_read<v_rd_off(D0, 3, 0)>(vb); X##7 = tr_read<v_rd_off(D0, 3, 1)>(vb); } while (0)
; #define LWAIT() do { asm volatile("s_waitcnt lgkmcnt(0)" ::: "memory"); SBAR(); } while (0)
; #define VMMP(D0, X) do { if (!(PROBE & 8)) VMM(D0, X); } while (0)
; #define SMXP(c) do { if (!(PROBE & 2)) { if (more) SMX_CH(c); } } while (0)
; template <int PROBE, int MODE>
; DI void dattn_body(const u16* __restrict__ Qb, const u16* __restrict__ Kh, const u16* __restrict__ Vh, u16* __restrict__ Ob, const u16* __restrict__ O1, float lam, const float* __restrict__ subg, int seq, int q0, float kmax2, char* lds) {
;     ...
;     LWAIT(); VRD(1, vc); VMMP(0, va); SMXP(0);
;     LWAIT(); VRD(2, va); VMMP(1, vc); SMXP(1);
;     LWAIT(); VRD(3, vc); VMMP(2, va); SMXP(2);
;     LWAIT(); VMMP(3, vc); SMXP(3);
;     if (!(PROBE & 2)) { if (more) SMX_FIN((j + 1) & 1); }
;     DMAWAIT();
;     __syncthreads();
.Lfast1_k_done:
	s_waitcnt lgkmcnt(6)
	v_mfma_f32_32x32x16_bf16 v[0:15], v[118:121], v[234:237], v[0:15]
	ds_read_b64_tr_b16 v[138:139], v215 offset:0x200
	ds_read_b64_tr_b16 v[140:141], v215 offset:0xa00
	s_waitcnt lgkmcnt(6)
	v_mfma_f32_32x32x16_bf16 v[0:15], v[122:125], v[238:241], v[0:15]
	ds_read_b64_tr_b16 v[142:143], v215 offset:0x1200
	ds_read_b64_tr_b16 v[144:145], v215 offset:0x1a00
	s_nop 1
	v_fma_f32 v162, v64, s12, v160
	v_fma_f32 v163, v65, s12, v160
	v_fma_f32 v164, v66, s12, v160
	v_fma_f32 v165, v67, s12, v160
	s_waitcnt lgkmcnt(6)
	v_mfma_f32_32x32x16_bf16 v[0:15], v[126:129], v[242:245], v[0:15]
	ds_read_b64_tr_b16 v[134:135], v215 offset:0x2200
	ds_read_b64_tr_b16 v[136:137], v215 offset:0x2a00
	v_fma_f32 v166, v68, s12, v160
	v_fma_f32 v167, v69, s12, v160
	v_exp_f32_e32 v162, v162
	v_exp_f32_e32 v163, v163
	s_waitcnt lgkmcnt(6)
	v_mfma_f32_32x32x16_bf16 v[0:15], v[114:117], v[246:249], v[0:15]
	ds_read_b64_tr_b16 v[130:131], v215 offset:0x3200
	ds_read_b64_tr_b16 v[132:133], v215 offset:0x3a00
	v_fma_f32 v168, v70, s12, v160
	v_fma_f32 v169, v71, s12, v160
	v_exp_f32_e32 v164, v164
	v_exp_f32_e32 v165, v165
	s_waitcnt lgkmcnt(6)
	v_mfma_f32_32x32x16_bf16 v[16:31], v[118:121], v[138:141], v[16:31]
	ds_read_b64_tr_b16 v[146:147], v215 offset:0x400
	ds_read_b64_tr_b16 v[148:149], v215 offset:0xc00
	v_exp_f32_e32 v166, v166
	v_exp_f32_e32 v167, v167
	v_add_f32_e32 v208, v162, v208
	v_add_f32_e32 v208, v163, v208
	s_waitcnt lgkmcnt(6)
	v_mfma_f32_32x32x16_bf16 v[16:31], v[122:125], v[142:145], v[16:31]
	ds_read_b64_tr_b16 v[142:143], v215 offset:0x1400
	ds_read_b64_tr_b16 v[144:145], v215 offset:0x1c00
	v_exp_f32_e32 v168, v168
	v_exp_f32_e32 v169, v169
	v_add_f32_e32 v208, v164, v208
	v_add_f32_e32 v208, v165, v208
	v_fma_f32 v244, v72, s12, v160
	v_fma_f32 v245, v73, s12, v160
	s_waitcnt lgkmcnt(6)
	v_mfma_f32_32x32x16_bf16 v[16:31], v[126:129], v[134:137], v[16:31]
	ds_read_b64_tr_b16 v[138:139], v215 offset:0x2400
	ds_read_b64_tr_b16 v[140:141], v215 offset:0x2c00
	v_fma_f32 v246, v74, s12, v160
	v_fma_f32 v247, v75, s12, v160
	v_add_f32_e32 v208, v166, v208
	v_add_f32_e32 v208, v167, v208
	s_waitcnt lgkmcnt(6)
	v_mfma_f32_32x32x16_bf16 v[16:31], v[114:117], v[130:133], v[16:31]
	ds_read_b64_tr_b16 v[64:65], v215 offset:0x3400
	ds_read_b64_tr_b16 v[66:67], v215 offset:0x3c00
	v_fma_f32 v76, v76, s12, v160
	v_fma_f32 v77, v77, s12, v160
	v_fma_f32 v78, v78, s12, v160
	v_fma_f32 v79, v79, s12, v160
	s_waitcnt lgkmcnt(6)
	v_mfma_f32_32x32x16_bf16 v[32:47], v[118:121], v[146:149], v[32:47]
	v_exp_f32_e32 v244, v244
	v_exp_f32_e32 v245, v245
	v_add_f32_e32 v208, v168, v208
	v_add_f32_e32 v208, v169, v208
	v_cvt_pk_bf16_f32 v236, v162, v163
	v_cvt_pk_bf16_f32 v237, v164, v165
	s_waitcnt lgkmcnt(4)
	v_mfma_f32_32x32x16_bf16 v[32:47], v[122:125], v[142:145], v[32:47]
	ds_read_b64_tr_b16 v[142:143], v215 offset:0x600
	ds_read_b64_tr_b16 v[144:145], v215 offset:0xe00
	ds_read_b64_tr_b16 v[130:131], v215 offset:0x1600
	ds_read_b64_tr_b16 v[132:133], v215 offset:0x1e00
	v_exp_f32_e32 v246, v246
	v_exp_f32_e32 v247, v247
	v_cvt_pk_bf16_f32 v238, v166, v167
	v_cvt_pk_bf16_f32 v239, v168, v169
	s_waitcnt lgkmcnt(6)
	v_mfma_f32_32x32x16_bf16 v[32:47], v[126:129], v[138:141], v[32:47]
	ds_read_b64_tr_b16 v[134:135], v215 offset:0x2600
	ds_read_b64_tr_b16 v[136:137], v215 offset:0x2e00
	v_exp_f32_e32 v76, v76
	v_exp_f32_e32 v77, v77
	v_add_f32_e32 v208, v244, v208
	v_add_f32_e32 v208, v245, v208
	v_permlane32_swap_b32_e32 v236, v238
	s_waitcnt lgkmcnt(6)
	v_mfma_f32_32x32x16_bf16 v[32:47], v[114:117], v[64:67], v[32:47]
	ds_read_b64_tr_b16 v[68:69], v215 offset:0x3600
	ds_read_b64_tr_b16 v[70:71], v215 offset:0x3e00
	v_exp_f32_e32 v78, v78
	v_exp_f32_e32 v79, v79
	v_add_f32_e32 v208, v246, v208
	v_add_f32_e32 v208, v247, v208
	v_permlane32_swap_b32_e32 v237, v239
	s_waitcnt lgkmcnt(6)
	v_mfma_f32_32x32x16_bf16 v[48:63], v[118:121], v[142:145], v[48:63]
	v_add_u32_e32 v64, s1, v210
	v_add_f32_e32 v208, v76, v208
	v_add_f32_e32 v208, v77, v208
	v_cvt_pk_bf16_f32 v240, v244, v245
	v_cvt_pk_bf16_f32 v241, v246, v247
	ds_write_b128 v64, v[236:239]
	s_waitcnt lgkmcnt(5)
	v_mfma_f32_32x32x16_bf16 v[48:63], v[122:125], v[130:133], v[48:63]
	v_add_f32_e32 v208, v78, v208
	v_add_f32_e32 v208, v79, v208
	v_cvt_pk_bf16_f32 v242, v76, v77
	v_cvt_pk_bf16_f32 v243, v78, v79
	s_waitcnt lgkmcnt(3)
	v_mfma_f32_32x32x16_bf16 v[48:63], v[126:129], v[134:137], v[48:63]
	v_permlane32_swap_b32_e32 v240, v242
	v_permlane32_swap_b32_e32 v241, v243
	s_waitcnt lgkmcnt(1)
	v_mfma_f32_32x32x16_bf16 v[48:63], v[114:117], v[68:71], v[48:63]
	ds_write_b128 v64, v[240:243] offset:16
	v_mov_b32_e32 v114, v236
	v_mov_b32_e32 v115, v237
	v_mov_b32_e32 v116, v238
	v_mov_b32_e32 v117, v239
	v_mov_b32_e32 v130, v240
	v_mov_b32_e32 v131, v241
	v_mov_b32_e32 v132, v242
	v_mov_b32_e32 v133, v243
	s_add_i32 s40, s40, 1
	s_add_i32 s0, s0, 64
	s_add_i32 s25, s25, 0x8000
	s_cmp_eq_u32 s83, s40
	s_waitcnt vmcnt(0) lgkmcnt(0)
	s_barrier
	s_cbranch_scc1 .LBB0_303
	s_branch .LBB0_285
